# group-norm phase: the fifth (sample) rows are spread one per pair of workgroups instead of all on 16 workgroups
# baseline (speedup 1.0000x reference)
.LBB0_1350:
	s_cmp_lt_i32 s56, 6
	s_cselect_b64 s[4:5], -1, 0
	s_and_b64 s[4:5], s[4:5], s[0:1]
	s_andn2_b64 vcc, exec, s[4:5]
	v_lshrrev_b32_e32 v167, 6, v166
	s_cbranch_vccnz .LBB0_1355
	s_waitcnt vmcnt(0)
	v_lshl_add_u32 v2, s2, 3, v167
	s_mov_b32 s0, 0x20800
	v_cmp_gt_i32_e32 vcc, s0, v2
	s_and_saveexec_b64 s[6:7], vcc
	v_readlane_b32 s36, v239, 49
	v_readlane_b32 s38, v239, 51
	v_readlane_b32 s39, v239, 52
	v_readlane_b32 s40, v239, 53
	v_readlane_b32 s41, v239, 54
	v_readlane_b32 s37, v239, 50
	v_readlane_b32 s42, v239, 55
	v_readlane_b32 s43, v239, 56
	v_readlane_b32 s44, v239, 57
	v_readlane_b32 s45, v239, 58
	v_readlane_b32 s46, v239, 59
	v_readlane_b32 s47, v239, 60
	v_readlane_b32 s48, v239, 61
	v_readlane_b32 s49, v239, 62
	v_readlane_b32 s50, v239, 63
	v_readlane_b32 s51, v238, 0
	s_cbranch_execz .LBB0_1354
	v_and_b32_e32 v0, 63, v166
	v_mov_b32_e32 v3, 0x3a27c5ac
	v_lshlrev_b32_e32 v1, 5, v0
	v_lshlrev_b32_e32 v2, 6, v0
	v_readfirstlane_b32 s0, v167
	s_add_u32 s10, s94, 0x6a00000
	s_addc_u32 s11, s95, 0
	s_add_u32 s8, s94, 0x800000
	s_addc_u32 s9, s95, 0
	s_lshl_b32 s3, s2, 3
	s_add_i32 s3, s3, s0
	s_lshr_b32 s12, s3, 4
	s_sub_i32 s13, s3, s12
	s_addk_i32 s13, 0x7f
	s_and_b32 s14, s3, 15
	s_cmp_eq_u32 s14, 0
	s_cselect_b32 s3, s12, s13
	global_load_dwordx4 v[132:135], v2, s[38:39]
	global_load_dwordx4 v[136:139], v2, s[38:39] offset:16
	global_load_dwordx4 v[140:143], v2, s[38:39] offset:32
	global_load_dwordx4 v[144:147], v2, s[38:39] offset:48
	global_load_dwordx4 v[148:151], v2, s[40:41]
	global_load_dwordx4 v[152:155], v2, s[40:41] offset:16
	global_load_dwordx4 v[156:159], v2, s[40:41] offset:32
	global_load_dwordx4 v[160:163], v2, s[40:41] offset:48
	s_mov_b32 s12, s3
	s_lshl_b32 s13, s12, 12
	s_add_u32 s14, s10, s13
	s_addc_u32 s15, s11, 0
	s_lshl_b32 s13, s12, 11
	s_add_u32 s16, s92, s13
	s_addc_u32 s17, s93, 0
	s_add_u32 s0, s8, s13
	s_addc_u32 s1, s9, 0
	global_load_dwordx4 v[4:7], v1, s[14:15]
	global_load_dwordx4 v[8:11], v1, s[14:15] offset:16
	global_load_dwordx4 v[12:15], v1, s[16:17]
	global_load_dwordx4 v[16:19], v1, s[16:17] offset:16
	global_load_dwordx4 v[20:23], v1, s[0:1]
	global_load_dwordx4 v[24:27], v1, s[0:1] offset:16
	s_add_i32 s12, s3, 2048
	s_lshl_b32 s13, s12, 12
	s_add_u32 s14, s10, s13
	s_addc_u32 s15, s11, 0
	s_lshl_b32 s13, s12, 11
	s_add_u32 s16, s92, s13
	s_addc_u32 s17, s93, 0
	s_add_u32 s0, s8, s13
	s_addc_u32 s1, s9, 0
	global_load_dwordx4 v[28:31], v1, s[14:15]
	global_load_dwordx4 v[32:35], v1, s[14:15] offset:16
	global_load_dwordx4 v[36:39], v1, s[16:17]
	global_load_dwordx4 v[40:43], v1, s[16:17] offset:16
	global_load_dwordx4 v[44:47], v1, s[0:1]
	global_load_dwordx4 v[48:51], v1, s[0:1] offset:16
	s_add_i32 s12, s3, 4096
	s_lshl_b32 s13, s12, 12
	s_add_u32 s14, s10, s13
	s_addc_u32 s15, s11, 0
	s_lshl_b32 s13, s12, 11
	s_add_u32 s16, s92, s13
	s_addc_u32 s17, s93, 0
	s_add_u32 s0, s8, s13
	s_addc_u32 s1, s9, 0
	global_load_dwordx4 v[52:55], v1, s[14:15]
	global_load_dwordx4 v[56:59], v1, s[14:15] offset:16
	global_load_dwordx4 v[60:63], v1, s[16:17]
	global_load_dwordx4 v[64:67], v1, s[16:17] offset:16
	global_load_dwordx4 v[68:71], v1, s[0:1]
	global_load_dwordx4 v[72:75], v1, s[0:1] offset:16
	s_add_i32 s12, s3, 6144
	s_lshl_b32 s13, s12, 12
	s_add_u32 s14, s10, s13
	s_addc_u32 s15, s11, 0
	s_lshl_b32 s13, s12, 11
	s_add_u32 s16, s92, s13
	s_addc_u32 s17, s93, 0
	s_add_u32 s0, s8, s13
	s_addc_u32 s1, s9, 0
	global_load_dwordx4 v[76:79], v1, s[14:15]
	global_load_dwordx4 v[80:83], v1, s[14:15] offset:16
	global_load_dwordx4 v[84:87], v1, s[16:17]
	global_load_dwordx4 v[88:91], v1, s[16:17] offset:16
	global_load_dwordx4 v[92:95], v1, s[0:1]
	global_load_dwordx4 v[96:99], v1, s[0:1] offset:16
	s_add_i32 s12, s3, 0x2000
	s_cmpk_lt_i32 s12, 0x2080
	s_cselect_b32 s12, s12, s3
	s_lshl_b32 s13, s12, 12
	s_add_u32 s14, s10, s13
	s_addc_u32 s15, s11, 0
	s_lshl_b32 s13, s12, 11
	s_add_u32 s16, s92, s13
	s_addc_u32 s17, s93, 0
	s_add_u32 s0, s8, s13
	s_addc_u32 s1, s9, 0
	global_load_dwordx4 v[100:103], v1, s[14:15]
	global_load_dwordx4 v[104:107], v1, s[14:15] offset:16
	global_load_dwordx4 v[108:111], v1, s[16:17]
	global_load_dwordx4 v[112:115], v1, s[16:17] offset:16
	global_load_dwordx4 v[116:119], v1, s[0:1]
	global_load_dwordx4 v[120:123], v1, s[0:1] offset:16
	s_waitcnt vmcnt(24)
	v_lshlrev_b32_e32 v168, 16, v4
	v_and_b32_e32 v169, 0xffff0000, v4
	v_lshlrev_b32_e32 v170, 16, v5
	v_and_b32_e32 v171, 0xffff0000, v5
	v_lshlrev_b32_e32 v172, 16, v6
	v_and_b32_e32 v173, 0xffff0000, v6
	v_lshlrev_b32_e32 v174, 16, v7
	v_and_b32_e32 v175, 0xffff0000, v7
	v_lshlrev_b32_e32 v176, 16, v8
	v_and_b32_e32 v177, 0xffff0000, v8
	v_lshlrev_b32_e32 v178, 16, v9
	v_and_b32_e32 v179, 0xffff0000, v9
	v_lshlrev_b32_e32 v180, 16, v10
	v_and_b32_e32 v181, 0xffff0000, v10
	v_lshlrev_b32_e32 v182, 16, v11
	v_and_b32_e32 v183, 0xffff0000, v11
	v_pk_add_f32 v[184:185], v[168:169], v[170:171]
	v_pk_add_f32 v[186:187], v[172:173], v[174:175]
	v_pk_add_f32 v[188:189], v[176:177], v[178:179]
	v_pk_add_f32 v[190:191], v[180:181], v[182:183]
	v_pk_add_f32 v[184:185], v[184:185], v[186:187]
	v_pk_add_f32 v[188:189], v[188:189], v[190:191]
	v_pk_add_f32 v[184:185], v[184:185], v[188:189]
	v_add_f32_e32 v192, v184, v185
	s_nop 1
	v_add_f32_dpp v192, v192, v192 quad_perm:[1,0,3,2] row_mask:0xf bank_mask:0xf bound_ctrl:1
	s_nop 1
	v_add_f32_dpp v192, v192, v192 quad_perm:[2,3,0,1] row_mask:0xf bank_mask:0xf bound_ctrl:1
	v_mul_f32_e32 v194, 0x3c800000, v192
	v_pk_add_f32 v[168:169], v[168:169], v[194:195] op_sel_hi:[1,0] neg_lo:[0,1] neg_hi:[0,1]
	v_pk_add_f32 v[170:171], v[170:171], v[194:195] op_sel_hi:[1,0] neg_lo:[0,1] neg_hi:[0,1]
	v_pk_add_f32 v[172:173], v[172:173], v[194:195] op_sel_hi:[1,0] neg_lo:[0,1] neg_hi:[0,1]
	v_pk_add_f32 v[174:175], v[174:175], v[194:195] op_sel_hi:[1,0] neg_lo:[0,1] neg_hi:[0,1]
	v_pk_add_f32 v[176:177], v[176:177], v[194:195] op_sel_hi:[1,0] neg_lo:[0,1] neg_hi:[0,1]
	v_pk_add_f32 v[178:179], v[178:179], v[194:195] op_sel_hi:[1,0] neg_lo:[0,1] neg_hi:[0,1]
	v_pk_add_f32 v[180:181], v[180:181], v[194:195] op_sel_hi:[1,0] neg_lo:[0,1] neg_hi:[0,1]
	v_pk_add_f32 v[182:183], v[182:183], v[194:195] op_sel_hi:[1,0] neg_lo:[0,1] neg_hi:[0,1]
	v_pk_mul_f32 v[184:185], v[168:169], v[168:169]
	v_pk_mul_f32 v[186:187], v[170:171], v[170:171]
	v_pk_fma_f32 v[184:185], v[172:173], v[172:173], v[184:185]
	v_pk_fma_f32 v[186:187], v[174:175], v[174:175], v[186:187]
	v_pk_fma_f32 v[184:185], v[176:177], v[176:177], v[184:185]
	v_pk_fma_f32 v[186:187], v[178:179], v[178:179], v[186:187]
	v_pk_fma_f32 v[184:185], v[180:181], v[180:181], v[184:185]
	v_pk_fma_f32 v[186:187], v[182:183], v[182:183], v[186:187]
	v_pk_add_f32 v[184:185], v[184:185], v[186:187]
	v_add_f32_e32 v192, v184, v185
	s_nop 1
	v_add_f32_dpp v192, v192, v192 quad_perm:[1,0,3,2] row_mask:0xf bank_mask:0xf bound_ctrl:1
	s_nop 1
	v_add_f32_dpp v192, v192, v192 quad_perm:[2,3,0,1] row_mask:0xf bank_mask:0xf bound_ctrl:1
	v_fmamk_f32 v196, v192, 0x3c800000, v3
	v_rsq_f32_e32 v196, v196
	s_mov_b32 s12, s3
	s_lshl_b32 s13, s12, 12
	s_add_u32 s14, s10, s13
	s_addc_u32 s15, s11, 0
	v_pk_mul_f32 v[212:213], v[168:169], v[196:197] op_sel_hi:[1,0]
	v_lshlrev_b32_e32 v208, 16, v12
	v_and_b32_e32 v209, 0xffff0000, v12
	v_pk_fma_f32 v[212:213], v[212:213], v[132:133], v[148:149]
	v_lshlrev_b32_e32 v210, 16, v20
	v_and_b32_e32 v211, 0xffff0000, v20
	v_pk_add_f32 v[212:213], v[212:213], v[208:209]
	v_pk_mul_f32 v[212:213], v[212:213], v[210:211]
	v_cvt_pk_bf16_f32 v200, v212, v213
	v_pk_mul_f32 v[212:213], v[170:171], v[196:197] op_sel_hi:[1,0]
	v_lshlrev_b32_e32 v208, 16, v13
	v_and_b32_e32 v209, 0xffff0000, v13
	v_pk_fma_f32 v[212:213], v[212:213], v[134:135], v[150:151]
	v_lshlrev_b32_e32 v210, 16, v21
	v_and_b32_e32 v211, 0xffff0000, v21
	v_pk_add_f32 v[212:213], v[212:213], v[208:209]
	v_pk_mul_f32 v[212:213], v[212:213], v[210:211]
	v_cvt_pk_bf16_f32 v201, v212, v213
	v_pk_mul_f32 v[212:213], v[172:173], v[196:197] op_sel_hi:[1,0]
	v_lshlrev_b32_e32 v208, 16, v14
	v_and_b32_e32 v209, 0xffff0000, v14
	v_pk_fma_f32 v[212:213], v[212:213], v[136:137], v[152:153]
	v_lshlrev_b32_e32 v210, 16, v22
	v_and_b32_e32 v211, 0xffff0000, v22
	v_pk_add_f32 v[212:213], v[212:213], v[208:209]
	v_pk_mul_f32 v[212:213], v[212:213], v[210:211]
	v_cvt_pk_bf16_f32 v202, v212, v213
	v_pk_mul_f32 v[212:213], v[174:175], v[196:197] op_sel_hi:[1,0]
	v_lshlrev_b32_e32 v208, 16, v15
	v_and_b32_e32 v209, 0xffff0000, v15
	v_pk_fma_f32 v[212:213], v[212:213], v[138:139], v[154:155]
	v_lshlrev_b32_e32 v210, 16, v23
	v_and_b32_e32 v211, 0xffff0000, v23
	v_pk_add_f32 v[212:213], v[212:213], v[208:209]
	v_pk_mul_f32 v[212:213], v[212:213], v[210:211]
	v_cvt_pk_bf16_f32 v203, v212, v213
	v_pk_mul_f32 v[212:213], v[176:177], v[196:197] op_sel_hi:[1,0]
	v_lshlrev_b32_e32 v208, 16, v16
	v_and_b32_e32 v209, 0xffff0000, v16
	v_pk_fma_f32 v[212:213], v[212:213], v[140:141], v[156:157]
	v_lshlrev_b32_e32 v210, 16, v24
	v_and_b32_e32 v211, 0xffff0000, v24
	v_pk_add_f32 v[212:213], v[212:213], v[208:209]
	v_pk_mul_f32 v[212:213], v[212:213], v[210:211]
	v_cvt_pk_bf16_f32 v204, v212, v213
	v_pk_mul_f32 v[212:213], v[178:179], v[196:197] op_sel_hi:[1,0]
	v_lshlrev_b32_e32 v208, 16, v17
	v_and_b32_e32 v209, 0xffff0000, v17
	v_pk_fma_f32 v[212:213], v[212:213], v[142:143], v[158:159]
	v_lshlrev_b32_e32 v210, 16, v25
	v_and_b32_e32 v211, 0xffff0000, v25
	v_pk_add_f32 v[212:213], v[212:213], v[208:209]
	v_pk_mul_f32 v[212:213], v[212:213], v[210:211]
	v_cvt_pk_bf16_f32 v205, v212, v213
	v_pk_mul_f32 v[212:213], v[180:181], v[196:197] op_sel_hi:[1,0]
	v_lshlrev_b32_e32 v208, 16, v18
	v_and_b32_e32 v209, 0xffff0000, v18
	v_pk_fma_f32 v[212:213], v[212:213], v[144:145], v[160:161]
	v_lshlrev_b32_e32 v210, 16, v26
	v_and_b32_e32 v211, 0xffff0000, v26
	v_pk_add_f32 v[212:213], v[212:213], v[208:209]
	v_pk_mul_f32 v[212:213], v[212:213], v[210:211]
	v_cvt_pk_bf16_f32 v206, v212, v213
	v_pk_mul_f32 v[212:213], v[182:183], v[196:197] op_sel_hi:[1,0]
	v_lshlrev_b32_e32 v208, 16, v19
	v_and_b32_e32 v209, 0xffff0000, v19
	v_pk_fma_f32 v[212:213], v[212:213], v[146:147], v[162:163]
	v_lshlrev_b32_e32 v210, 16, v27
	v_and_b32_e32 v211, 0xffff0000, v27
	v_pk_add_f32 v[212:213], v[212:213], v[208:209]
	v_pk_mul_f32 v[212:213], v[212:213], v[210:211]
	v_cvt_pk_bf16_f32 v207, v212, v213
	global_store_dwordx4 v1, v[200:203], s[14:15]
	global_store_dwordx4 v1, v[204:207], s[14:15] offset:16
	s_waitcnt vmcnt(20)
	v_lshlrev_b32_e32 v168, 16, v28
	v_and_b32_e32 v169, 0xffff0000, v28
	v_lshlrev_b32_e32 v170, 16, v29
	v_and_b32_e32 v171, 0xffff0000, v29
	v_lshlrev_b32_e32 v172, 16, v30
	v_and_b32_e32 v173, 0xffff0000, v30
	v_lshlrev_b32_e32 v174, 16, v31
	v_and_b32_e32 v175, 0xffff0000, v31
	v_lshlrev_b32_e32 v176, 16, v32
	v_and_b32_e32 v177, 0xffff0000, v32
	v_lshlrev_b32_e32 v178, 16, v33
	v_and_b32_e32 v179, 0xffff0000, v33
	v_lshlrev_b32_e32 v180, 16, v34
	v_and_b32_e32 v181, 0xffff0000, v34
	v_lshlrev_b32_e32 v182, 16, v35
	v_and_b32_e32 v183, 0xffff0000, v35
	v_pk_add_f32 v[184:185], v[168:169], v[170:171]
	v_pk_add_f32 v[186:187], v[172:173], v[174:175]
	v_pk_add_f32 v[188:189], v[176:177], v[178:179]
	v_pk_add_f32 v[190:191], v[180:181], v[182:183]
	v_pk_add_f32 v[184:185], v[184:185], v[186:187]
	v_pk_add_f32 v[188:189], v[188:189], v[190:191]
	v_pk_add_f32 v[184:185], v[184:185], v[188:189]
	v_add_f32_e32 v192, v184, v185
	s_nop 1
	v_add_f32_dpp v192, v192, v192 quad_perm:[1,0,3,2] row_mask:0xf bank_mask:0xf bound_ctrl:1
	s_nop 1
	v_add_f32_dpp v192, v192, v192 quad_perm:[2,3,0,1] row_mask:0xf bank_mask:0xf bound_ctrl:1
	v_mul_f32_e32 v194, 0x3c800000, v192
	v_pk_add_f32 v[168:169], v[168:169], v[194:195] op_sel_hi:[1,0] neg_lo:[0,1] neg_hi:[0,1]
	v_pk_add_f32 v[170:171], v[170:171], v[194:195] op_sel_hi:[1,0] neg_lo:[0,1] neg_hi:[0,1]
	v_pk_add_f32 v[172:173], v[172:173], v[194:195] op_sel_hi:[1,0] neg_lo:[0,1] neg_hi:[0,1]
	v_pk_add_f32 v[174:175], v[174:175], v[194:195] op_sel_hi:[1,0] neg_lo:[0,1] neg_hi:[0,1]
	v_pk_add_f32 v[176:177], v[176:177], v[194:195] op_sel_hi:[1,0] neg_lo:[0,1] neg_hi:[0,1]
	v_pk_add_f32 v[178:179], v[178:179], v[194:195] op_sel_hi:[1,0] neg_lo:[0,1] neg_hi:[0,1]
	v_pk_add_f32 v[180:181], v[180:181], v[194:195] op_sel_hi:[1,0] neg_lo:[0,1] neg_hi:[0,1]
	v_pk_add_f32 v[182:183], v[182:183], v[194:195] op_sel_hi:[1,0] neg_lo:[0,1] neg_hi:[0,1]
	v_pk_mul_f32 v[184:185], v[168:169], v[168:169]
	v_pk_mul_f32 v[186:187], v[170:171], v[170:171]
	v_pk_fma_f32 v[184:185], v[172:173], v[172:173], v[184:185]
	v_pk_fma_f32 v[186:187], v[174:175], v[174:175], v[186:187]
	v_pk_fma_f32 v[184:185], v[176:177], v[176:177], v[184:185]
	v_pk_fma_f32 v[186:187], v[178:179], v[178:179], v[186:187]
	v_pk_fma_f32 v[184:185], v[180:181], v[180:181], v[184:185]
	v_pk_fma_f32 v[186:187], v[182:183], v[182:183], v[186:187]
	v_pk_add_f32 v[184:185], v[184:185], v[186:187]
	v_add_f32_e32 v192, v184, v185
	s_nop 1
	v_add_f32_dpp v192, v192, v192 quad_perm:[1,0,3,2] row_mask:0xf bank_mask:0xf bound_ctrl:1
	s_nop 1
	v_add_f32_dpp v192, v192, v192 quad_perm:[2,3,0,1] row_mask:0xf bank_mask:0xf bound_ctrl:1
	v_fmamk_f32 v196, v192, 0x3c800000, v3
	v_rsq_f32_e32 v196, v196
	s_add_i32 s12, s3, 2048
	s_lshl_b32 s13, s12, 12
	s_add_u32 s14, s10, s13
	s_addc_u32 s15, s11, 0
	v_pk_mul_f32 v[212:213], v[168:169], v[196:197] op_sel_hi:[1,0]
	v_lshlrev_b32_e32 v208, 16, v36
	v_and_b32_e32 v209, 0xffff0000, v36
	v_pk_fma_f32 v[212:213], v[212:213], v[132:133], v[148:149]
	v_lshlrev_b32_e32 v210, 16, v44
	v_and_b32_e32 v211, 0xffff0000, v44
	v_pk_add_f32 v[212:213], v[212:213], v[208:209]
	v_pk_mul_f32 v[212:213], v[212:213], v[210:211]
	v_cvt_pk_bf16_f32 v200, v212, v213
	v_pk_mul_f32 v[212:213], v[170:171], v[196:197] op_sel_hi:[1,0]
	v_lshlrev_b32_e32 v208, 16, v37
	v_and_b32_e32 v209, 0xffff0000, v37
	v_pk_fma_f32 v[212:213], v[212:213], v[134:135], v[150:151]
	v_lshlrev_b32_e32 v210, 16, v45
	v_and_b32_e32 v211, 0xffff0000, v45
	v_pk_add_f32 v[212:213], v[212:213], v[208:209]
	v_pk_mul_f32 v[212:213], v[212:213], v[210:211]
	v_cvt_pk_bf16_f32 v201, v212, v213
	v_pk_mul_f32 v[212:213], v[172:173], v[196:197] op_sel_hi:[1,0]
	v_lshlrev_b32_e32 v208, 16, v38
	v_and_b32_e32 v209, 0xffff0000, v38
	v_pk_fma_f32 v[212:213], v[212:213], v[136:137], v[152:153]
	v_lshlrev_b32_e32 v210, 16, v46
	v_and_b32_e32 v211, 0xffff0000, v46
	v_pk_add_f32 v[212:213], v[212:213], v[208:209]
	v_pk_mul_f32 v[212:213], v[212:213], v[210:211]
	v_cvt_pk_bf16_f32 v202, v212, v213
	v_pk_mul_f32 v[212:213], v[174:175], v[196:197] op_sel_hi:[1,0]
	v_lshlrev_b32_e32 v208, 16, v39
	v_and_b32_e32 v209, 0xffff0000, v39
	v_pk_fma_f32 v[212:213], v[212:213], v[138:139], v[154:155]
	v_lshlrev_b32_e32 v210, 16, v47
	v_and_b32_e32 v211, 0xffff0000, v47
	v_pk_add_f32 v[212:213], v[212:213], v[208:209]
	v_pk_mul_f32 v[212:213], v[212:213], v[210:211]
	v_cvt_pk_bf16_f32 v203, v212, v213
	v_pk_mul_f32 v[212:213], v[176:177], v[196:197] op_sel_hi:[1,0]
	v_lshlrev_b32_e32 v208, 16, v40
	v_and_b32_e32 v209, 0xffff0000, v40
	v_pk_fma_f32 v[212:213], v[212:213], v[140:141], v[156:157]
	v_lshlrev_b32_e32 v210, 16, v48
	v_and_b32_e32 v211, 0xffff0000, v48
	v_pk_add_f32 v[212:213], v[212:213], v[208:209]
	v_pk_mul_f32 v[212:213], v[212:213], v[210:211]
	v_cvt_pk_bf16_f32 v204, v212, v213
	v_pk_mul_f32 v[212:213], v[178:179], v[196:197] op_sel_hi:[1,0]
	v_lshlrev_b32_e32 v208, 16, v41
	v_and_b32_e32 v209, 0xffff0000, v41
	v_pk_fma_f32 v[212:213], v[212:213], v[142:143], v[158:159]
	v_lshlrev_b32_e32 v210, 16, v49
	v_and_b32_e32 v211, 0xffff0000, v49
	v_pk_add_f32 v[212:213], v[212:213], v[208:209]
	v_pk_mul_f32 v[212:213], v[212:213], v[210:211]
	v_cvt_pk_bf16_f32 v205, v212, v213
	v_pk_mul_f32 v[212:213], v[180:181], v[196:197] op_sel_hi:[1,0]
	v_lshlrev_b32_e32 v208, 16, v42
	v_and_b32_e32 v209, 0xffff0000, v42
	v_pk_fma_f32 v[212:213], v[212:213], v[144:145], v[160:161]
	v_lshlrev_b32_e32 v210, 16, v50
	v_and_b32_e32 v211, 0xffff0000, v50
	v_pk_add_f32 v[212:213], v[212:213], v[208:209]
	v_pk_mul_f32 v[212:213], v[212:213], v[210:211]
	v_cvt_pk_bf16_f32 v206, v212, v213
	v_pk_mul_f32 v[212:213], v[182:183], v[196:197] op_sel_hi:[1,0]
	v_lshlrev_b32_e32 v208, 16, v43
	v_and_b32_e32 v209, 0xffff0000, v43
	v_pk_fma_f32 v[212:213], v[212:213], v[146:147], v[162:163]
	v_lshlrev_b32_e32 v210, 16, v51
	v_and_b32_e32 v211, 0xffff0000, v51
	v_pk_add_f32 v[212:213], v[212:213], v[208:209]
	v_pk_mul_f32 v[212:213], v[212:213], v[210:211]
	v_cvt_pk_bf16_f32 v207, v212, v213
	global_store_dwordx4 v1, v[200:203], s[14:15]
	global_store_dwordx4 v1, v[204:207], s[14:15] offset:16
	s_waitcnt vmcnt(16)
	v_lshlrev_b32_e32 v168, 16, v52
	v_and_b32_e32 v169, 0xffff0000, v52
	v_lshlrev_b32_e32 v170, 16, v53
	v_and_b32_e32 v171, 0xffff0000, v53
	v_lshlrev_b32_e32 v172, 16, v54
	v_and_b32_e32 v173, 0xffff0000, v54
	v_lshlrev_b32_e32 v174, 16, v55
	v_and_b32_e32 v175, 0xffff0000, v55
	v_lshlrev_b32_e32 v176, 16, v56
	v_and_b32_e32 v177, 0xffff0000, v56
	v_lshlrev_b32_e32 v178, 16, v57
	v_and_b32_e32 v179, 0xffff0000, v57
	v_lshlrev_b32_e32 v180, 16, v58
	v_and_b32_e32 v181, 0xffff0000, v58
	v_lshlrev_b32_e32 v182, 16, v59
	v_and_b32_e32 v183, 0xffff0000, v59
	v_pk_add_f32 v[184:185], v[168:169], v[170:171]
	v_pk_add_f32 v[186:187], v[172:173], v[174:175]
	v_pk_add_f32 v[188:189], v[176:177], v[178:179]
	v_pk_add_f32 v[190:191], v[180:181], v[182:183]
	v_pk_add_f32 v[184:185], v[184:185], v[186:187]
	v_pk_add_f32 v[188:189], v[188:189], v[190:191]
	v_pk_add_f32 v[184:185], v[184:185], v[188:189]
	v_add_f32_e32 v192, v184, v185
	s_nop 1
	v_add_f32_dpp v192, v192, v192 quad_perm:[1,0,3,2] row_mask:0xf bank_mask:0xf bound_ctrl:1
	s_nop 1
	v_add_f32_dpp v192, v192, v192 quad_perm:[2,3,0,1] row_mask:0xf bank_mask:0xf bound_ctrl:1
	v_mul_f32_e32 v194, 0x3c800000, v192
	v_pk_add_f32 v[168:169], v[168:169], v[194:195] op_sel_hi:[1,0] neg_lo:[0,1] neg_hi:[0,1]
	v_pk_add_f32 v[170:171], v[170:171], v[194:195] op_sel_hi:[1,0] neg_lo:[0,1] neg_hi:[0,1]
	v_pk_add_f32 v[172:173], v[172:173], v[194:195] op_sel_hi:[1,0] neg_lo:[0,1] neg_hi:[0,1]
	v_pk_add_f32 v[174:175], v[174:175], v[194:195] op_sel_hi:[1,0] neg_lo:[0,1] neg_hi:[0,1]
	v_pk_add_f32 v[176:177], v[176:177], v[194:195] op_sel_hi:[1,0] neg_lo:[0,1] neg_hi:[0,1]
	v_pk_add_f32 v[178:179], v[178:179], v[194:195] op_sel_hi:[1,0] neg_lo:[0,1] neg_hi:[0,1]
	v_pk_add_f32 v[180:181], v[180:181], v[194:195] op_sel_hi:[1,0] neg_lo:[0,1] neg_hi:[0,1]
	v_pk_add_f32 v[182:183], v[182:183], v[194:195] op_sel_hi:[1,0] neg_lo:[0,1] neg_hi:[0,1]
	v_pk_mul_f32 v[184:185], v[168:169], v[168:169]
	v_pk_mul_f32 v[186:187], v[170:171], v[170:171]
	v_pk_fma_f32 v[184:185], v[172:173], v[172:173], v[184:185]
	v_pk_fma_f32 v[186:187], v[174:175], v[174:175], v[186:187]
	v_pk_fma_f32 v[184:185], v[176:177], v[176:177], v[184:185]
	v_pk_fma_f32 v[186:187], v[178:179], v[178:179], v[186:187]
	v_pk_fma_f32 v[184:185], v[180:181], v[180:181], v[184:185]
	v_pk_fma_f32 v[186:187], v[182:183], v[182:183], v[186:187]
	v_pk_add_f32 v[184:185], v[184:185], v[186:187]
	v_add_f32_e32 v192, v184, v185
	s_nop 1
	v_add_f32_dpp v192, v192, v192 quad_perm:[1,0,3,2] row_mask:0xf bank_mask:0xf bound_ctrl:1
	s_nop 1
	v_add_f32_dpp v192, v192, v192 quad_perm:[2,3,0,1] row_mask:0xf bank_mask:0xf bound_ctrl:1
	v_fmamk_f32 v196, v192, 0x3c800000, v3
	v_rsq_f32_e32 v196, v196
	s_add_i32 s12, s3, 4096
	s_lshl_b32 s13, s12, 12
	s_add_u32 s14, s10, s13
	s_addc_u32 s15, s11, 0
	v_pk_mul_f32 v[212:213], v[168:169], v[196:197] op_sel_hi:[1,0]
	v_lshlrev_b32_e32 v208, 16, v60
	v_and_b32_e32 v209, 0xffff0000, v60
	v_pk_fma_f32 v[212:213], v[212:213], v[132:133], v[148:149]
	v_lshlrev_b32_e32 v210, 16, v68
	v_and_b32_e32 v211, 0xffff0000, v68
	v_pk_add_f32 v[212:213], v[212:213], v[208:209]
	v_pk_mul_f32 v[212:213], v[212:213], v[210:211]
	v_cvt_pk_bf16_f32 v200, v212, v213
	v_pk_mul_f32 v[212:213], v[170:171], v[196:197] op_sel_hi:[1,0]
	v_lshlrev_b32_e32 v208, 16, v61
	v_and_b32_e32 v209, 0xffff0000, v61
	v_pk_fma_f32 v[212:213], v[212:213], v[134:135], v[150:151]
	v_lshlrev_b32_e32 v210, 16, v69
	v_and_b32_e32 v211, 0xffff0000, v69
	v_pk_add_f32 v[212:213], v[212:213], v[208:209]
	v_pk_mul_f32 v[212:213], v[212:213], v[210:211]
	v_cvt_pk_bf16_f32 v201, v212, v213
	v_pk_mul_f32 v[212:213], v[172:173], v[196:197] op_sel_hi:[1,0]
	v_lshlrev_b32_e32 v208, 16, v62
	v_and_b32_e32 v209, 0xffff0000, v62
	v_pk_fma_f32 v[212:213], v[212:213], v[136:137], v[152:153]
	v_lshlrev_b32_e32 v210, 16, v70
	v_and_b32_e32 v211, 0xffff0000, v70
	v_pk_add_f32 v[212:213], v[212:213], v[208:209]
	v_pk_mul_f32 v[212:213], v[212:213], v[210:211]
	v_cvt_pk_bf16_f32 v202, v212, v213
	v_pk_mul_f32 v[212:213], v[174:175], v[196:197] op_sel_hi:[1,0]
	v_lshlrev_b32_e32 v208, 16, v63
	v_and_b32_e32 v209, 0xffff0000, v63
	v_pk_fma_f32 v[212:213], v[212:213], v[138:139], v[154:155]
	v_lshlrev_b32_e32 v210, 16, v71
	v_and_b32_e32 v211, 0xffff0000, v71
	v_pk_add_f32 v[212:213], v[212:213], v[208:209]
	v_pk_mul_f32 v[212:213], v[212:213], v[210:211]
	v_cvt_pk_bf16_f32 v203, v212, v213
	v_pk_mul_f32 v[212:213], v[176:177], v[196:197] op_sel_hi:[1,0]
	v_lshlrev_b32_e32 v208, 16, v64
	v_and_b32_e32 v209, 0xffff0000, v64
	v_pk_fma_f32 v[212:213], v[212:213], v[140:141], v[156:157]
	v_lshlrev_b32_e32 v210, 16, v72
	v_and_b32_e32 v211, 0xffff0000, v72
	v_pk_add_f32 v[212:213], v[212:213], v[208:209]
	v_pk_mul_f32 v[212:213], v[212:213], v[210:211]
	v_cvt_pk_bf16_f32 v204, v212, v213
	v_pk_mul_f32 v[212:213], v[178:179], v[196:197] op_sel_hi:[1,0]
	v_lshlrev_b32_e32 v208, 16, v65
	v_and_b32_e32 v209, 0xffff0000, v65
	v_pk_fma_f32 v[212:213], v[212:213], v[142:143], v[158:159]
	v_lshlrev_b32_e32 v210, 16, v73
	v_and_b32_e32 v211, 0xffff0000, v73
	v_pk_add_f32 v[212:213], v[212:213], v[208:209]
	v_pk_mul_f32 v[212:213], v[212:213], v[210:211]
	v_cvt_pk_bf16_f32 v205, v212, v213
	v_pk_mul_f32 v[212:213], v[180:181], v[196:197] op_sel_hi:[1,0]
	v_lshlrev_b32_e32 v208, 16, v66
	v_and_b32_e32 v209, 0xffff0000, v66
	v_pk_fma_f32 v[212:213], v[212:213], v[144:145], v[160:161]
	v_lshlrev_b32_e32 v210, 16, v74
	v_and_b32_e32 v211, 0xffff0000, v74
	v_pk_add_f32 v[212:213], v[212:213], v[208:209]
	v_pk_mul_f32 v[212:213], v[212:213], v[210:211]
	v_cvt_pk_bf16_f32 v206, v212, v213
	v_pk_mul_f32 v[212:213], v[182:183], v[196:197] op_sel_hi:[1,0]
	v_lshlrev_b32_e32 v208, 16, v67
	v_and_b32_e32 v209, 0xffff0000, v67
	v_pk_fma_f32 v[212:213], v[212:213], v[146:147], v[162:163]
	v_lshlrev_b32_e32 v210, 16, v75
	v_and_b32_e32 v211, 0xffff0000, v75
	v_pk_add_f32 v[212:213], v[212:213], v[208:209]
	v_pk_mul_f32 v[212:213], v[212:213], v[210:211]
	v_cvt_pk_bf16_f32 v207, v212, v213
	global_store_dwordx4 v1, v[200:203], s[14:15]
	global_store_dwordx4 v1, v[204:207], s[14:15] offset:16
	s_waitcnt vmcnt(12)
	v_lshlrev_b32_e32 v168, 16, v76
	v_and_b32_e32 v169, 0xffff0000, v76
	v_lshlrev_b32_e32 v170, 16, v77
	v_and_b32_e32 v171, 0xffff0000, v77
	v_lshlrev_b32_e32 v172, 16, v78
	v_and_b32_e32 v173, 0xffff0000, v78
	v_lshlrev_b32_e32 v174, 16, v79
	v_and_b32_e32 v175, 0xffff0000, v79
	v_lshlrev_b32_e32 v176, 16, v80
	v_and_b32_e32 v177, 0xffff0000, v80
	v_lshlrev_b32_e32 v178, 16, v81
	v_and_b32_e32 v179, 0xffff0000, v81
	v_lshlrev_b32_e32 v180, 16, v82
	v_and_b32_e32 v181, 0xffff0000, v82
	v_lshlrev_b32_e32 v182, 16, v83
	v_and_b32_e32 v183, 0xffff0000, v83
	v_pk_add_f32 v[184:185], v[168:169], v[170:171]
	v_pk_add_f32 v[186:187], v[172:173], v[174:175]
	v_pk_add_f32 v[188:189], v[176:177], v[178:179]
	v_pk_add_f32 v[190:191], v[180:181], v[182:183]
	v_pk_add_f32 v[184:185], v[184:185], v[186:187]
	v_pk_add_f32 v[188:189], v[188:189], v[190:191]
	v_pk_add_f32 v[184:185], v[184:185], v[188:189]
	v_add_f32_e32 v192, v184, v185
	s_nop 1
	v_add_f32_dpp v192, v192, v192 quad_perm:[1,0,3,2] row_mask:0xf bank_mask:0xf bound_ctrl:1
	s_nop 1
	v_add_f32_dpp v192, v192, v192 quad_perm:[2,3,0,1] row_mask:0xf bank_mask:0xf bound_ctrl:1
	v_mul_f32_e32 v194, 0x3c800000, v192
	v_pk_add_f32 v[168:169], v[168:169], v[194:195] op_sel_hi:[1,0] neg_lo:[0,1] neg_hi:[0,1]
	v_pk_add_f32 v[170:171], v[170:171], v[194:195] op_sel_hi:[1,0] neg_lo:[0,1] neg_hi:[0,1]
	v_pk_add_f32 v[172:173], v[172:173], v[194:195] op_sel_hi:[1,0] neg_lo:[0,1] neg_hi:[0,1]
	v_pk_add_f32 v[174:175], v[174:175], v[194:195] op_sel_hi:[1,0] neg_lo:[0,1] neg_hi:[0,1]
	v_pk_add_f32 v[176:177], v[176:177], v[194:195] op_sel_hi:[1,0] neg_lo:[0,1] neg_hi:[0,1]
	v_pk_add_f32 v[178:179], v[178:179], v[194:195] op_sel_hi:[1,0] neg_lo:[0,1] neg_hi:[0,1]
	v_pk_add_f32 v[180:181], v[180:181], v[194:195] op_sel_hi:[1,0] neg_lo:[0,1] neg_hi:[0,1]
	v_pk_add_f32 v[182:183], v[182:183], v[194:195] op_sel_hi:[1,0] neg_lo:[0,1] neg_hi:[0,1]
	v_pk_mul_f32 v[184:185], v[168:169], v[168:169]
	v_pk_mul_f32 v[186:187], v[170:171], v[170:171]
	v_pk_fma_f32 v[184:185], v[172:173], v[172:173], v[184:185]
	v_pk_fma_f32 v[186:187], v[174:175], v[174:175], v[186:187]
	v_pk_fma_f32 v[184:185], v[176:177], v[176:177], v[184:185]
	v_pk_fma_f32 v[186:187], v[178:179], v[178:179], v[186:187]
	v_pk_fma_f32 v[184:185], v[180:181], v[180:181], v[184:185]
	v_pk_fma_f32 v[186:187], v[182:183], v[182:183], v[186:187]
	v_pk_add_f32 v[184:185], v[184:185], v[186:187]
	v_add_f32_e32 v192, v184, v185
	s_nop 1
	v_add_f32_dpp v192, v192, v192 quad_perm:[1,0,3,2] row_mask:0xf bank_mask:0xf bound_ctrl:1
	s_nop 1
	v_add_f32_dpp v192, v192, v192 quad_perm:[2,3,0,1] row_mask:0xf bank_mask:0xf bound_ctrl:1
	v_fmamk_f32 v196, v192, 0x3c800000, v3
	v_rsq_f32_e32 v196, v196
	s_add_i32 s12, s3, 6144
	s_lshl_b32 s13, s12, 12
	s_add_u32 s14, s10, s13
	s_addc_u32 s15, s11, 0
	v_pk_mul_f32 v[212:213], v[168:169], v[196:197] op_sel_hi:[1,0]
	v_lshlrev_b32_e32 v208, 16, v84
	v_and_b32_e32 v209, 0xffff0000, v84
	v_pk_fma_f32 v[212:213], v[212:213], v[132:133], v[148:149]
	v_lshlrev_b32_e32 v210, 16, v92
	v_and_b32_e32 v211, 0xffff0000, v92
	v_pk_add_f32 v[212:213], v[212:213], v[208:209]
	v_pk_mul_f32 v[212:213], v[212:213], v[210:211]
	v_cvt_pk_bf16_f32 v200, v212, v213
	v_pk_mul_f32 v[212:213], v[170:171], v[196:197] op_sel_hi:[1,0]
	v_lshlrev_b32_e32 v208, 16, v85
	v_and_b32_e32 v209, 0xffff0000, v85
	v_pk_fma_f32 v[212:213], v[212:213], v[134:135], v[150:151]
	v_lshlrev_b32_e32 v210, 16, v93
	v_and_b32_e32 v211, 0xffff0000, v93
	v_pk_add_f32 v[212:213], v[212:213], v[208:209]
	v_pk_mul_f32 v[212:213], v[212:213], v[210:211]
	v_cvt_pk_bf16_f32 v201, v212, v213
	v_pk_mul_f32 v[212:213], v[172:173], v[196:197] op_sel_hi:[1,0]
	v_lshlrev_b32_e32 v208, 16, v86
	v_and_b32_e32 v209, 0xffff0000, v86
	v_pk_fma_f32 v[212:213], v[212:213], v[136:137], v[152:153]
	v_lshlrev_b32_e32 v210, 16, v94
	v_and_b32_e32 v211, 0xffff0000, v94
	v_pk_add_f32 v[212:213], v[212:213], v[208:209]
	v_pk_mul_f32 v[212:213], v[212:213], v[210:211]
	v_cvt_pk_bf16_f32 v202, v212, v213
	v_pk_mul_f32 v[212:213], v[174:175], v[196:197] op_sel_hi:[1,0]
	v_lshlrev_b32_e32 v208, 16, v87
	v_and_b32_e32 v209, 0xffff0000, v87
	v_pk_fma_f32 v[212:213], v[212:213], v[138:139], v[154:155]
	v_lshlrev_b32_e32 v210, 16, v95
	v_and_b32_e32 v211, 0xffff0000, v95
	v_pk_add_f32 v[212:213], v[212:213], v[208:209]
	v_pk_mul_f32 v[212:213], v[212:213], v[210:211]
	v_cvt_pk_bf16_f32 v203, v212, v213
	v_pk_mul_f32 v[212:213], v[176:177], v[196:197] op_sel_hi:[1,0]
	v_lshlrev_b32_e32 v208, 16, v88
	v_and_b32_e32 v209, 0xffff0000, v88
	v_pk_fma_f32 v[212:213], v[212:213], v[140:141], v[156:157]
	v_lshlrev_b32_e32 v210, 16, v96
	v_and_b32_e32 v211, 0xffff0000, v96
	v_pk_add_f32 v[212:213], v[212:213], v[208:209]
	v_pk_mul_f32 v[212:213], v[212:213], v[210:211]
	v_cvt_pk_bf16_f32 v204, v212, v213
	v_pk_mul_f32 v[212:213], v[178:179], v[196:197] op_sel_hi:[1,0]
	v_lshlrev_b32_e32 v208, 16, v89
	v_and_b32_e32 v209, 0xffff0000, v89
	v_pk_fma_f32 v[212:213], v[212:213], v[142:143], v[158:159]
	v_lshlrev_b32_e32 v210, 16, v97
	v_and_b32_e32 v211, 0xffff0000, v97
	v_pk_add_f32 v[212:213], v[212:213], v[208:209]
	v_pk_mul_f32 v[212:213], v[212:213], v[210:211]
	v_cvt_pk_bf16_f32 v205, v212, v213
	v_pk_mul_f32 v[212:213], v[180:181], v[196:197] op_sel_hi:[1,0]
	v_lshlrev_b32_e32 v208, 16, v90
	v_and_b32_e32 v209, 0xffff0000, v90
	v_pk_fma_f32 v[212:213], v[212:213], v[144:145], v[160:161]
	v_lshlrev_b32_e32 v210, 16, v98
	v_and_b32_e32 v211, 0xffff0000, v98
	v_pk_add_f32 v[212:213], v[212:213], v[208:209]
	v_pk_mul_f32 v[212:213], v[212:213], v[210:211]
	v_cvt_pk_bf16_f32 v206, v212, v213
	v_pk_mul_f32 v[212:213], v[182:183], v[196:197] op_sel_hi:[1,0]
	v_lshlrev_b32_e32 v208, 16, v91
	v_and_b32_e32 v209, 0xffff0000, v91
	v_pk_fma_f32 v[212:213], v[212:213], v[146:147], v[162:163]
	v_lshlrev_b32_e32 v210, 16, v99
	v_and_b32_e32 v211, 0xffff0000, v99
	v_pk_add_f32 v[212:213], v[212:213], v[208:209]
	v_pk_mul_f32 v[212:213], v[212:213], v[210:211]
	v_cvt_pk_bf16_f32 v207, v212, v213
	global_store_dwordx4 v1, v[200:203], s[14:15]
	global_store_dwordx4 v1, v[204:207], s[14:15] offset:16
	s_add_i32 s12, s3, 0x2000
	s_cmpk_lt_i32 s12, 0x2080
	s_cbranch_scc0 .Lgn_done
	s_waitcnt vmcnt(8)
	v_lshlrev_b32_e32 v168, 16, v100
	v_and_b32_e32 v169, 0xffff0000, v100
	v_lshlrev_b32_e32 v170, 16, v101
	v_and_b32_e32 v171, 0xffff0000, v101
	v_lshlrev_b32_e32 v172, 16, v102
	v_and_b32_e32 v173, 0xffff0000, v102
	v_lshlrev_b32_e32 v174, 16, v103
	v_and_b32_e32 v175, 0xffff0000, v103
	v_lshlrev_b32_e32 v176, 16, v104
	v_and_b32_e32 v177, 0xffff0000, v104
	v_lshlrev_b32_e32 v178, 16, v105
	v_and_b32_e32 v179, 0xffff0000, v105
	v_lshlrev_b32_e32 v180, 16, v106
	v_and_b32_e32 v181, 0xffff0000, v106
	v_lshlrev_b32_e32 v182, 16, v107
	v_and_b32_e32 v183, 0xffff0000, v107
	v_pk_add_f32 v[184:185], v[168:169], v[170:171]
	v_pk_add_f32 v[186:187], v[172:173], v[174:175]
	v_pk_add_f32 v[188:189], v[176:177], v[178:179]
	v_pk_add_f32 v[190:191], v[180:181], v[182:183]
	v_pk_add_f32 v[184:185], v[184:185], v[186:187]
	v_pk_add_f32 v[188:189], v[188:189], v[190:191]
	v_pk_add_f32 v[184:185], v[184:185], v[188:189]
	v_add_f32_e32 v192, v184, v185
	s_nop 1
	v_add_f32_dpp v192, v192, v192 quad_perm:[1,0,3,2] row_mask:0xf bank_mask:0xf bound_ctrl:1
	s_nop 1
	v_add_f32_dpp v192, v192, v192 quad_perm:[2,3,0,1] row_mask:0xf bank_mask:0xf bound_ctrl:1
	v_mul_f32_e32 v194, 0x3c800000, v192
	v_pk_add_f32 v[168:169], v[168:169], v[194:195] op_sel_hi:[1,0] neg_lo:[0,1] neg_hi:[0,1]
	v_pk_add_f32 v[170:171], v[170:171], v[194:195] op_sel_hi:[1,0] neg_lo:[0,1] neg_hi:[0,1]
	v_pk_add_f32 v[172:173], v[172:173], v[194:195] op_sel_hi:[1,0] neg_lo:[0,1] neg_hi:[0,1]
	v_pk_add_f32 v[174:175], v[174:175], v[194:195] op_sel_hi:[1,0] neg_lo:[0,1] neg_hi:[0,1]
	v_pk_add_f32 v[176:177], v[176:177], v[194:195] op_sel_hi:[1,0] neg_lo:[0,1] neg_hi:[0,1]
	v_pk_add_f32 v[178:179], v[178:179], v[194:195] op_sel_hi:[1,0] neg_lo:[0,1] neg_hi:[0,1]
	v_pk_add_f32 v[180:181], v[180:181], v[194:195] op_sel_hi:[1,0] neg_lo:[0,1] neg_hi:[0,1]
	v_pk_add_f32 v[182:183], v[182:183], v[194:195] op_sel_hi:[1,0] neg_lo:[0,1] neg_hi:[0,1]
	v_pk_mul_f32 v[184:185], v[168:169], v[168:169]
	v_pk_mul_f32 v[186:187], v[170:171], v[170:171]
	v_pk_fma_f32 v[184:185], v[172:173], v[172:173], v[184:185]
	v_pk_fma_f32 v[186:187], v[174:175], v[174:175], v[186:187]
	v_pk_fma_f32 v[184:185], v[176:177], v[176:177], v[184:185]
	v_pk_fma_f32 v[186:187], v[178:179], v[178:179], v[186:187]
	v_pk_fma_f32 v[184:185], v[180:181], v[180:181], v[184:185]
	v_pk_fma_f32 v[186:187], v[182:183], v[182:183], v[186:187]
	v_pk_add_f32 v[184:185], v[184:185], v[186:187]
	v_add_f32_e32 v192, v184, v185
	s_nop 1
	v_add_f32_dpp v192, v192, v192 quad_perm:[1,0,3,2] row_mask:0xf bank_mask:0xf bound_ctrl:1
	s_nop 1
	v_add_f32_dpp v192, v192, v192 quad_perm:[2,3,0,1] row_mask:0xf bank_mask:0xf bound_ctrl:1
	v_fmamk_f32 v196, v192, 0x3c800000, v3
	v_rsq_f32_e32 v196, v196
	s_add_i32 s12, s3, 8192
	s_lshl_b32 s13, s12, 12
	s_add_u32 s14, s10, s13
	s_addc_u32 s15, s11, 0
	v_pk_mul_f32 v[212:213], v[168:169], v[196:197] op_sel_hi:[1,0]
	v_lshlrev_b32_e32 v208, 16, v108
	v_and_b32_e32 v209, 0xffff0000, v108
	v_pk_fma_f32 v[212:213], v[212:213], v[132:133], v[148:149]
	v_lshlrev_b32_e32 v210, 16, v116
	v_and_b32_e32 v211, 0xffff0000, v116
	v_pk_add_f32 v[212:213], v[212:213], v[208:209]
	v_pk_mul_f32 v[212:213], v[212:213], v[210:211]
	v_cvt_pk_bf16_f32 v200, v212, v213
	v_pk_mul_f32 v[212:213], v[170:171], v[196:197] op_sel_hi:[1,0]
	v_lshlrev_b32_e32 v208, 16, v109
	v_and_b32_e32 v209, 0xffff0000, v109
	v_pk_fma_f32 v[212:213], v[212:213], v[134:135], v[150:151]
	v_lshlrev_b32_e32 v210, 16, v117
	v_and_b32_e32 v211, 0xffff0000, v117
	v_pk_add_f32 v[212:213], v[212:213], v[208:209]
	v_pk_mul_f32 v[212:213], v[212:213], v[210:211]
	v_cvt_pk_bf16_f32 v201, v212, v213
	v_pk_mul_f32 v[212:213], v[172:173], v[196:197] op_sel_hi:[1,0]
	v_lshlrev_b32_e32 v208, 16, v110
	v_and_b32_e32 v209, 0xffff0000, v110
	v_pk_fma_f32 v[212:213], v[212:213], v[136:137], v[152:153]
	v_lshlrev_b32_e32 v210, 16, v118
	v_and_b32_e32 v211, 0xffff0000, v118
	v_pk_add_f32 v[212:213], v[212:213], v[208:209]
	v_pk_mul_f32 v[212:213], v[212:213], v[210:211]
	v_cvt_pk_bf16_f32 v202, v212, v213
	v_pk_mul_f32 v[212:213], v[174:175], v[196:197] op_sel_hi:[1,0]
	v_lshlrev_b32_e32 v208, 16, v111
	v_and_b32_e32 v209, 0xffff0000, v111
	v_pk_fma_f32 v[212:213], v[212:213], v[138:139], v[154:155]
	v_lshlrev_b32_e32 v210, 16, v119
	v_and_b32_e32 v211, 0xffff0000, v119
	v_pk_add_f32 v[212:213], v[212:213], v[208:209]
	v_pk_mul_f32 v[212:213], v[212:213], v[210:211]
	v_cvt_pk_bf16_f32 v203, v212, v213
	v_pk_mul_f32 v[212:213], v[176:177], v[196:197] op_sel_hi:[1,0]
	v_lshlrev_b32_e32 v208, 16, v112
	v_and_b32_e32 v209, 0xffff0000, v112
	v_pk_fma_f32 v[212:213], v[212:213], v[140:141], v[156:157]
	v_lshlrev_b32_e32 v210, 16, v120
	v_and_b32_e32 v211, 0xffff0000, v120
	v_pk_add_f32 v[212:213], v[212:213], v[208:209]
	v_pk_mul_f32 v[212:213], v[212:213], v[210:211]
	v_cvt_pk_bf16_f32 v204, v212, v213
	v_pk_mul_f32 v[212:213], v[178:179], v[196:197] op_sel_hi:[1,0]
	v_lshlrev_b32_e32 v208, 16, v113
	v_and_b32_e32 v209, 0xffff0000, v113
	v_pk_fma_f32 v[212:213], v[212:213], v[142:143], v[158:159]
	v_lshlrev_b32_e32 v210, 16, v121
	v_and_b32_e32 v211, 0xffff0000, v121
	v_pk_add_f32 v[212:213], v[212:213], v[208:209]
	v_pk_mul_f32 v[212:213], v[212:213], v[210:211]
	v_cvt_pk_bf16_f32 v205, v212, v213
	v_pk_mul_f32 v[212:213], v[180:181], v[196:197] op_sel_hi:[1,0]
	v_lshlrev_b32_e32 v208, 16, v114
	v_and_b32_e32 v209, 0xffff0000, v114
	v_pk_fma_f32 v[212:213], v[212:213], v[144:145], v[160:161]
	v_lshlrev_b32_e32 v210, 16, v122
	v_and_b32_e32 v211, 0xffff0000, v122
	v_pk_add_f32 v[212:213], v[212:213], v[208:209]
	v_pk_mul_f32 v[212:213], v[212:213], v[210:211]
	v_cvt_pk_bf16_f32 v206, v212, v213
	v_pk_mul_f32 v[212:213], v[182:183], v[196:197] op_sel_hi:[1,0]
	v_lshlrev_b32_e32 v208, 16, v115
	v_and_b32_e32 v209, 0xffff0000, v115
	v_pk_fma_f32 v[212:213], v[212:213], v[146:147], v[162:163]
	v_lshlrev_b32_e32 v210, 16, v123
	v_and_b32_e32 v211, 0xffff0000, v123
	v_pk_add_f32 v[212:213], v[212:213], v[208:209]
	v_pk_mul_f32 v[212:213], v[212:213], v[210:211]
	v_cvt_pk_bf16_f32 v207, v212, v213
	global_store_dwordx4 v1, v[200:203], s[14:15]
	global_store_dwordx4 v1, v[204:207], s[14:15] offset:16
